# in-proj: row statistics via LDS DMA and first K64 step peeled with C=0; gate GEMM: redundant vmcnt(0) before the K loop removed
# speedup vs baseline: 1.0096x; 1.0031x over previous
.LBB0_861:
	s_ashr_i32 s65, s64, 31
	s_lshl_b64 s[22:23], s[64:65], 19
	s_add_u32 s66, s80, s22
	s_addc_u32 s67, s81, s23
	s_and_b64 s[22:23], s[6:7], exec
	s_cselect_b32 s9, s67, s13
	s_cselect_b32 s11, s66, s12
	s_ashr_i32 s63, s62, 31
	s_lshl_b64 s[22:23], s[62:63], 19
	s_add_u32 s78, s84, s22
	s_addc_u32 s79, s85, s23
	s_and_b64 s[22:23], s[6:7], exec
	s_cselect_b32 s14, s79, s29
	s_cselect_b32 s22, s78, s28
	s_cmp_ge_u32 s87, 0x1000
	s_cbranch_scc1 .Lst3_skip
	s_lshl_b32 s30, s10, 12
	s_add_u32 s30, s20, s30
	s_addc_u32 s31, s21, 0
	s_and_b32 s23, s25, 1
	s_lshl_b32 s23, s23, 12
	s_add_i32 s23, s23, 0x20000
	s_add_i32 m0, s87, s23
	v_lshlrev_b32_e32 v154, 4, v0
	s_nop 0
	global_load_lds_dwordx4 v154, s[30:31]
.Lst3_skip:
	s_add_u32 s12, s12, 0x40080
	s_addc_u32 s13, s13, 0
	s_add_u32 s23, s28, 0x100
	s_addc_u32 s24, s29, 0
	s_mov_b32 s34, -2
	ds_read_b128 v[154:157], v141
	ds_read_b128 v[158:161], v141 offset:1024
	ds_read_b128 v[162:165], v141 offset:2048
	ds_read_b128 v[166:169], v141 offset:3072
	ds_read_b128 v[170:173], v182
	ds_read_b128 v[174:177], v182 offset:1024
	ds_read_b128 v[178:181], v182 offset:2048
	ds_read_b128 v[186:189], v182 offset:3072
	s_add_u32 s28, s12, 0xfffc0080
	s_addc_u32 s29, s13, -1
	s_cmp_eq_u32 s34, 12
	s_cselect_b32 s31, s9, s29
	s_cselect_b32 s30, s11, s28
	s_cselect_b32 s29, s14, s24
	s_cselect_b32 s28, s22, s23
	s_add_i32 m0, s87, 0xc000
	ds_read_b128 v[190:193], v183
	ds_read_b128 v[194:197], v183 offset:1024
	ds_read_b128 v[198:201], v183 offset:2048
	ds_read_b128 v[202:205], v183 offset:3072
	ds_read_b128 v[206:209], v183 offset:4096
	ds_read_b128 v[210:213], v183 offset:5120
	ds_read_b128 v[214:217], v183 offset:6144
	ds_read_b128 v[218:221], v183 offset:7168
	global_load_lds_dwordx4 v146, s[12:13]
	s_add_i32 m0, s87, 0xe000
	s_nop 0
	global_load_lds_dwordx4 v148, s[12:13]
	s_waitcnt vmcnt(8)
	s_waitcnt lgkmcnt(0)
	s_barrier
	v_mfma_f32_16x16x32_bf16 v[126:129], v[154:157], v[190:193], 0
	v_mfma_f32_16x16x32_bf16 v[122:125], v[162:165], v[190:193], 0
	v_mfma_f32_16x16x32_bf16 v[118:121], v[154:157], v[198:201], 0
	v_mfma_f32_16x16x32_bf16 v[114:117], v[162:165], v[198:201], 0
	v_mfma_f32_16x16x32_bf16 v[110:113], v[154:157], v[206:209], 0
	v_mfma_f32_16x16x32_bf16 v[106:109], v[162:165], v[206:209], 0
	v_mfma_f32_16x16x32_bf16 v[102:105], v[154:157], v[214:217], 0
	v_mfma_f32_16x16x32_bf16 v[98:101], v[162:165], v[214:217], 0
	v_mfma_f32_16x16x32_bf16 v[126:129], v[158:161], v[194:197], v[126:129]
	v_mfma_f32_16x16x32_bf16 v[122:125], v[166:169], v[194:197], v[122:125]
	v_mfma_f32_16x16x32_bf16 v[118:121], v[158:161], v[202:205], v[118:121]
	v_mfma_f32_16x16x32_bf16 v[114:117], v[166:169], v[202:205], v[114:117]
	v_mfma_f32_16x16x32_bf16 v[110:113], v[158:161], v[210:213], v[110:113]
	v_mfma_f32_16x16x32_bf16 v[106:109], v[166:169], v[210:213], v[106:109]
	v_mfma_f32_16x16x32_bf16 v[102:105], v[158:161], v[218:221], v[102:105]
	v_mfma_f32_16x16x32_bf16 v[98:101], v[166:169], v[218:221], v[98:101]
	v_mfma_f32_16x16x32_bf16 v[62:65], v[170:173], v[190:193], 0
	v_mfma_f32_16x16x32_bf16 v[58:61], v[178:181], v[190:193], 0
	v_mfma_f32_16x16x32_bf16 v[54:57], v[170:173], v[198:201], 0
	v_mfma_f32_16x16x32_bf16 v[50:53], v[178:181], v[198:201], 0
	v_mfma_f32_16x16x32_bf16 v[46:49], v[170:173], v[206:209], 0
	v_mfma_f32_16x16x32_bf16 v[42:45], v[178:181], v[206:209], 0
	v_mfma_f32_16x16x32_bf16 v[38:41], v[170:173], v[214:217], 0
	v_mfma_f32_16x16x32_bf16 v[34:37], v[178:181], v[214:217], 0
	v_mfma_f32_16x16x32_bf16 v[62:65], v[174:177], v[194:197], v[62:65]
	v_mfma_f32_16x16x32_bf16 v[58:61], v[186:189], v[194:197], v[58:61]
	v_mfma_f32_16x16x32_bf16 v[54:57], v[174:177], v[202:205], v[54:57]
	v_mfma_f32_16x16x32_bf16 v[50:53], v[186:189], v[202:205], v[50:53]
	v_mfma_f32_16x16x32_bf16 v[46:49], v[174:177], v[210:213], v[46:49]
	v_mfma_f32_16x16x32_bf16 v[42:45], v[186:189], v[210:213], v[42:45]
	v_mfma_f32_16x16x32_bf16 v[38:41], v[174:177], v[218:221], v[38:41]
	v_mfma_f32_16x16x32_bf16 v[34:37], v[186:189], v[218:221], v[34:37]
	s_barrier
	s_add_i32 s35, s97, s77
	s_mov_b32 m0, s35
	ds_read_b128 v[190:193], v183 offset:16384
	ds_read_b128 v[194:197], v183 offset:17408
	ds_read_b128 v[198:201], v183 offset:18432
	ds_read_b128 v[202:205], v183 offset:19456
	ds_read_b128 v[206:209], v183 offset:20480
	ds_read_b128 v[210:213], v183 offset:21504
	ds_read_b128 v[214:217], v183 offset:22528
	ds_read_b128 v[218:221], v183 offset:23552
	global_load_lds_dwordx4 v132, s[28:29]
	s_add_i32 m0, s35, 0x2000
	s_add_u32 s68, s28, 0x40000
	s_addc_u32 s69, s29, 0
	s_add_i32 s35, s74, s77
	global_load_lds_dwordx4 v136, s[28:29]
	s_mov_b32 m0, s35
	s_nop 0
	global_load_lds_dwordx4 v132, s[68:69]
	s_add_i32 m0, s35, 0x2000
	s_nop 0
	global_load_lds_dwordx4 v136, s[68:69]
	s_mov_b32 m0, s87
	s_nop 0
	global_load_lds_dwordx4 v130, s[30:31]
	s_mov_b32 m0, s88
	s_nop 0
	global_load_lds_dwordx4 v134, s[30:31]
	s_waitcnt vmcnt(8)
	s_waitcnt lgkmcnt(0)
	s_barrier
	v_mfma_f32_16x16x32_bf16 v[94:97], v[154:157], v[190:193], 0
	v_mfma_f32_16x16x32_bf16 v[90:93], v[162:165], v[190:193], 0
	v_mfma_f32_16x16x32_bf16 v[86:89], v[154:157], v[198:201], 0
	v_mfma_f32_16x16x32_bf16 v[82:85], v[162:165], v[198:201], 0
	v_mfma_f32_16x16x32_bf16 v[78:81], v[154:157], v[206:209], 0
	v_mfma_f32_16x16x32_bf16 v[74:77], v[162:165], v[206:209], 0
	v_mfma_f32_16x16x32_bf16 v[70:73], v[154:157], v[214:217], 0
	v_mfma_f32_16x16x32_bf16 v[66:69], v[162:165], v[214:217], 0
	v_mfma_f32_16x16x32_bf16 v[94:97], v[158:161], v[194:197], v[94:97]
	v_mfma_f32_16x16x32_bf16 v[90:93], v[166:169], v[194:197], v[90:93]
	v_mfma_f32_16x16x32_bf16 v[86:89], v[158:161], v[202:205], v[86:89]
	v_mfma_f32_16x16x32_bf16 v[82:85], v[166:169], v[202:205], v[82:85]
	v_mfma_f32_16x16x32_bf16 v[78:81], v[158:161], v[210:213], v[78:81]
	v_mfma_f32_16x16x32_bf16 v[74:77], v[166:169], v[210:213], v[74:77]
	v_mfma_f32_16x16x32_bf16 v[70:73], v[158:161], v[218:221], v[70:73]
	v_mfma_f32_16x16x32_bf16 v[66:69], v[166:169], v[218:221], v[66:69]
	v_mfma_f32_16x16x32_bf16 v[30:33], v[170:173], v[190:193], 0
	v_mfma_f32_16x16x32_bf16 v[26:29], v[178:181], v[190:193], 0
	v_mfma_f32_16x16x32_bf16 v[22:25], v[170:173], v[198:201], 0
	v_mfma_f32_16x16x32_bf16 v[18:21], v[178:181], v[198:201], 0
	v_mfma_f32_16x16x32_bf16 v[14:17], v[170:173], v[206:209], 0
	v_mfma_f32_16x16x32_bf16 v[10:13], v[178:181], v[206:209], 0
	v_mfma_f32_16x16x32_bf16 v[6:9], v[170:173], v[214:217], 0
	v_mfma_f32_16x16x32_bf16 v[2:5], v[178:181], v[214:217], 0
	v_mfma_f32_16x16x32_bf16 v[30:33], v[174:177], v[194:197], v[30:33]
	v_mfma_f32_16x16x32_bf16 v[26:29], v[186:189], v[194:197], v[26:29]
	v_mfma_f32_16x16x32_bf16 v[22:25], v[174:177], v[202:205], v[22:25]
	v_mfma_f32_16x16x32_bf16 v[18:21], v[186:189], v[202:205], v[18:21]
	v_mfma_f32_16x16x32_bf16 v[14:17], v[174:177], v[210:213], v[14:17]
	v_mfma_f32_16x16x32_bf16 v[10:13], v[186:189], v[210:213], v[10:13]
	v_mfma_f32_16x16x32_bf16 v[6:9], v[174:177], v[218:221], v[6:9]
	v_mfma_f32_16x16x32_bf16 v[2:5], v[186:189], v[218:221], v[2:5]
	s_barrier
	s_branch .Lpeel862_seg3

.Lpeel862_seg3:
	s_add_i32 s35, 0, 0x18000
	s_add_i32 s63, 0, 0x1c000
	v_add_u32_e32 v166, s35, v139
	v_add_u32_e32 v185, s63, v139
	ds_read_b128 v[154:157], v166
	ds_read_b128 v[158:161], v166 offset:1024
	ds_read_b128 v[162:165], v166 offset:2048
	ds_read_b128 v[166:169], v166 offset:3072
	ds_read_b128 v[170:173], v185
	ds_read_b128 v[174:177], v185 offset:1024
	ds_read_b128 v[178:181], v185 offset:2048
	ds_read_b128 v[186:189], v185 offset:3072
	s_add_u32 s98, s30, 0x40000
	s_addc_u32 s99, s31, 0
	s_mov_b32 m0, s89
	ds_read_b128 v[190:193], v183 offset:32768
	ds_read_b128 v[194:197], v183 offset:33792
	ds_read_b128 v[198:201], v183 offset:34816
	ds_read_b128 v[202:205], v183 offset:35840
	ds_read_b128 v[206:209], v183 offset:36864
	ds_read_b128 v[210:213], v183 offset:37888
	ds_read_b128 v[214:217], v183 offset:38912
	ds_read_b128 v[218:221], v183 offset:39936
	global_load_lds_dwordx4 v130, s[98:99]
	s_mov_b32 m0, s90
	s_nop 0
	global_load_lds_dwordx4 v134, s[98:99]
	s_waitcnt vmcnt(8)
	s_waitcnt lgkmcnt(0)
	s_barrier
	v_mfma_f32_16x16x32_bf16 v[126:129], v[154:157], v[190:193], v[126:129]
	v_mfma_f32_16x16x32_bf16 v[122:125], v[162:165], v[190:193], v[122:125]
	v_mfma_f32_16x16x32_bf16 v[118:121], v[154:157], v[198:201], v[118:121]
	v_mfma_f32_16x16x32_bf16 v[114:117], v[162:165], v[198:201], v[114:117]
	v_mfma_f32_16x16x32_bf16 v[110:113], v[154:157], v[206:209], v[110:113]
	v_mfma_f32_16x16x32_bf16 v[106:109], v[162:165], v[206:209], v[106:109]
	v_mfma_f32_16x16x32_bf16 v[102:105], v[154:157], v[214:217], v[102:105]
	v_mfma_f32_16x16x32_bf16 v[98:101], v[162:165], v[214:217], v[98:101]
	v_mfma_f32_16x16x32_bf16 v[126:129], v[158:161], v[194:197], v[126:129]
	v_mfma_f32_16x16x32_bf16 v[122:125], v[166:169], v[194:197], v[122:125]
	v_mfma_f32_16x16x32_bf16 v[118:121], v[158:161], v[202:205], v[118:121]
	v_mfma_f32_16x16x32_bf16 v[114:117], v[166:169], v[202:205], v[114:117]
	v_mfma_f32_16x16x32_bf16 v[110:113], v[158:161], v[210:213], v[110:113]
	v_mfma_f32_16x16x32_bf16 v[106:109], v[166:169], v[210:213], v[106:109]
	v_mfma_f32_16x16x32_bf16 v[102:105], v[158:161], v[218:221], v[102:105]
	v_mfma_f32_16x16x32_bf16 v[98:101], v[166:169], v[218:221], v[98:101]
	v_mfma_f32_16x16x32_bf16 v[62:65], v[170:173], v[190:193], v[62:65]
	v_mfma_f32_16x16x32_bf16 v[58:61], v[178:181], v[190:193], v[58:61]
	v_mfma_f32_16x16x32_bf16 v[54:57], v[170:173], v[198:201], v[54:57]
	v_mfma_f32_16x16x32_bf16 v[50:53], v[178:181], v[198:201], v[50:53]
	v_mfma_f32_16x16x32_bf16 v[46:49], v[170:173], v[206:209], v[46:49]
	v_mfma_f32_16x16x32_bf16 v[42:45], v[178:181], v[206:209], v[42:45]
	v_mfma_f32_16x16x32_bf16 v[38:41], v[170:173], v[214:217], v[38:41]
	v_mfma_f32_16x16x32_bf16 v[34:37], v[178:181], v[214:217], v[34:37]
	v_mfma_f32_16x16x32_bf16 v[62:65], v[174:177], v[194:197], v[62:65]
	v_mfma_f32_16x16x32_bf16 v[58:61], v[186:189], v[194:197], v[58:61]
	v_mfma_f32_16x16x32_bf16 v[54:57], v[174:177], v[202:205], v[54:57]
	v_mfma_f32_16x16x32_bf16 v[50:53], v[186:189], v[202:205], v[50:53]
	v_mfma_f32_16x16x32_bf16 v[46:49], v[174:177], v[210:213], v[46:49]
	v_mfma_f32_16x16x32_bf16 v[42:45], v[186:189], v[210:213], v[42:45]
	v_mfma_f32_16x16x32_bf16 v[38:41], v[174:177], v[218:221], v[38:41]
	v_mfma_f32_16x16x32_bf16 v[34:37], v[186:189], v[218:221], v[34:37]
	s_barrier
	s_add_i32 s98, s35, s77
	s_add_i32 m0, s98, 0xffffff80
	ds_read_b128 v[190:193], v183 offset:49152
	ds_read_b128 v[194:197], v183 offset:50176
	ds_read_b128 v[198:201], v183 offset:51200
	ds_read_b128 v[202:205], v183 offset:52224
	ds_read_b128 v[206:209], v183 offset:53248
	ds_read_b128 v[210:213], v183 offset:54272
	ds_read_b128 v[214:217], v183 offset:55296
	ds_read_b128 v[218:221], v183 offset:56320
	global_load_lds_dwordx4 v132, s[28:29] offset:128
	s_add_i32 m0, s98, 0x1f80
	s_add_i32 s98, s63, s77
	global_load_lds_dwordx4 v136, s[28:29] offset:128
	s_add_u32 s28, s28, 0x40080
	s_addc_u32 s29, s29, 0
	s_mov_b32 m0, s98
	s_nop 0
	global_load_lds_dwordx4 v132, s[28:29]
	s_add_i32 m0, s98, 0x2000
	s_nop 0
	global_load_lds_dwordx4 v136, s[28:29]
	s_add_i32 m0, s92, 0xffffff80
	s_nop 0
	global_load_lds_dwordx4 v130, s[30:31] offset:128
	s_add_i32 m0, s93, 0xffffff80
	s_nop 0
	global_load_lds_dwordx4 v134, s[30:31] offset:128
	s_waitcnt vmcnt(8)
	s_waitcnt lgkmcnt(0)
	s_barrier
	v_mfma_f32_16x16x32_bf16 v[94:97], v[154:157], v[190:193], v[94:97]
	v_mfma_f32_16x16x32_bf16 v[90:93], v[162:165], v[190:193], v[90:93]
	v_mfma_f32_16x16x32_bf16 v[86:89], v[154:157], v[198:201], v[86:89]
	v_mfma_f32_16x16x32_bf16 v[82:85], v[162:165], v[198:201], v[82:85]
	v_mfma_f32_16x16x32_bf16 v[78:81], v[154:157], v[206:209], v[78:81]
	v_mfma_f32_16x16x32_bf16 v[74:77], v[162:165], v[206:209], v[74:77]
	v_mfma_f32_16x16x32_bf16 v[70:73], v[154:157], v[214:217], v[70:73]
	v_mfma_f32_16x16x32_bf16 v[66:69], v[162:165], v[214:217], v[66:69]
	v_mfma_f32_16x16x32_bf16 v[94:97], v[158:161], v[194:197], v[94:97]
	v_mfma_f32_16x16x32_bf16 v[90:93], v[166:169], v[194:197], v[90:93]
	v_mfma_f32_16x16x32_bf16 v[86:89], v[158:161], v[202:205], v[86:89]
	v_mfma_f32_16x16x32_bf16 v[82:85], v[166:169], v[202:205], v[82:85]
	v_mfma_f32_16x16x32_bf16 v[78:81], v[158:161], v[210:213], v[78:81]
	v_mfma_f32_16x16x32_bf16 v[74:77], v[166:169], v[210:213], v[74:77]
	v_mfma_f32_16x16x32_bf16 v[70:73], v[158:161], v[218:221], v[70:73]
	v_mfma_f32_16x16x32_bf16 v[66:69], v[166:169], v[218:221], v[66:69]
	v_mfma_f32_16x16x32_bf16 v[30:33], v[170:173], v[190:193], v[30:33]
	v_mfma_f32_16x16x32_bf16 v[26:29], v[178:181], v[190:193], v[26:29]
	v_mfma_f32_16x16x32_bf16 v[22:25], v[170:173], v[198:201], v[22:25]
	v_mfma_f32_16x16x32_bf16 v[18:21], v[178:181], v[198:201], v[18:21]
	v_mfma_f32_16x16x32_bf16 v[14:17], v[170:173], v[206:209], v[14:17]
	v_mfma_f32_16x16x32_bf16 v[10:13], v[178:181], v[206:209], v[10:13]
	v_mfma_f32_16x16x32_bf16 v[6:9], v[170:173], v[214:217], v[6:9]
	v_mfma_f32_16x16x32_bf16 v[2:5], v[178:181], v[214:217], v[2:5]
	v_mfma_f32_16x16x32_bf16 v[30:33], v[174:177], v[194:197], v[30:33]
	v_mfma_f32_16x16x32_bf16 v[26:29], v[186:189], v[194:197], v[26:29]
	v_mfma_f32_16x16x32_bf16 v[22:25], v[174:177], v[202:205], v[22:25]
	v_mfma_f32_16x16x32_bf16 v[18:21], v[186:189], v[202:205], v[18:21]
	v_mfma_f32_16x16x32_bf16 v[14:17], v[174:177], v[210:213], v[14:17]
	v_mfma_f32_16x16x32_bf16 v[10:13], v[186:189], v[210:213], v[10:13]
	v_mfma_f32_16x16x32_bf16 v[6:9], v[174:177], v[218:221], v[6:9]
	v_mfma_f32_16x16x32_bf16 v[2:5], v[186:189], v[218:221], v[2:5]
	s_barrier
	s_add_i32 s34, s34, 2
	s_add_u32 s12, s12, 0x100
	s_addc_u32 s13, s13, 0
	s_add_u32 s23, s23, 0x100
	s_addc_u32 s24, s24, 0
	s_cmp_gt_u32 s34, 13
	s_cbranch_scc0 .LBB0_862
	s_and_b64 vcc, exec, s[54:55]
	s_cbranch_vccz .LBB0_865
	s_barrier

.LBB0_880:
	s_lshl_b32 s22, s10, 8
	s_add_i32 s22, s22, s91
	v_or_b32_e32 v168, s22, v1
	s_and_b32 s23, s25, 1
	s_lshl_b32 s23, s23, 12
	s_add_i32 s23, s23, 0x20000
	s_lshl_b32 s24, s91, 4
	s_add_i32 s23, s23, s24
	v_lshl_add_u32 v206, v1, 4, s23
	v_or_b32_e32 v166, 16, v168
	v_ashrrev_i32_e32 v169, 31, v168
	v_ashrrev_i32_e32 v167, 31, v166
	v_or_b32_e32 v164, 32, v168
	v_or_b32_e32 v162, 48, v168
	v_ashrrev_i32_e32 v165, 31, v164
	v_ashrrev_i32_e32 v163, 31, v162
	v_add_u32_e32 v160, 0x80, v168
	v_add_u32_e32 v158, 0x90, v168
	ds_read_b128 v[170:173], v206
	ds_read_b128 v[174:177], v206 offset:256
	v_ashrrev_i32_e32 v161, 31, v160
	v_ashrrev_i32_e32 v159, 31, v158
	ds_read_b128 v[178:181], v206 offset:512
	ds_read_b128 v[186:189], v206 offset:768
	ds_read_b128 v[190:193], v206 offset:2048
	ds_read_b128 v[194:197], v206 offset:2304
	v_add_u32_e32 v156, 0xa0, v168
	v_ashrrev_i32_e32 v157, 31, v156
	ds_read_b128 v[198:201], v206 offset:2560
	v_add_u32_e32 v154, 0xb0, v168
	v_ashrrev_i32_e32 v155, 31, v154
	ds_read_b128 v[202:205], v206 offset:2816
	s_lshl_b32 s23, s8, 2
	s_or_b32 s24, s23, s94
	s_cmp_lt_i32 s24, 56
	s_mov_b64 s[8:9], -1
	s_waitcnt lgkmcnt(0)
	v_add_f32_e32 v170, v170, v171
	v_add_f32_e32 v171, v172, v173
	v_add_f32_e32 v170, v170, v171
	v_add_f32_e32 v171, v174, v175
	v_add_f32_e32 v172, v176, v177
	v_add_f32_e32 v173, v178, v179
	v_add_f32_e32 v174, v180, v181
	v_add_f32_e32 v175, v186, v187
	v_add_f32_e32 v176, v188, v189
	v_add_f32_e32 v177, v190, v191
	v_add_f32_e32 v178, v192, v193
	v_add_f32_e32 v179, v194, v195
	v_add_f32_e32 v180, v196, v197
	v_add_f32_e32 v181, v198, v199
	v_add_f32_e32 v185, v200, v201
	v_fmamk_f32 v170, v170, 0x3a800000, v184
	v_add_f32_e32 v171, v171, v172
	v_add_f32_e32 v186, v202, v203
	v_add_f32_e32 v187, v204, v205
	v_add_f32_e32 v172, v173, v174
	v_add_f32_e32 v173, v175, v176
	v_add_f32_e32 v174, v177, v178
	v_add_f32_e32 v175, v179, v180
	v_add_f32_e32 v176, v181, v185
	v_add_f32_e32 v177, v186, v187
	v_rsq_f32_e32 v192, v170
	v_fmamk_f32 v170, v171, 0x3a800000, v184
	v_fmamk_f32 v171, v172, 0x3a800000, v184
	v_fmamk_f32 v172, v173, 0x3a800000, v184
	v_fmamk_f32 v173, v174, 0x3a800000, v184
	v_fmamk_f32 v174, v175, 0x3a800000, v184
	v_fmamk_f32 v175, v176, 0x3a800000, v184
	v_fmamk_f32 v176, v177, 0x3a800000, v184
	v_rsq_f32_e32 v191, v170
	v_rsq_f32_e32 v190, v171
	v_rsq_f32_e32 v189, v172
	v_rsq_f32_e32 v188, v173
	v_rsq_f32_e32 v187, v174
	v_rsq_f32_e32 v186, v175
	v_rsq_f32_e32 v185, v176
	s_cbranch_scc1 .LBB0_884
	s_and_b64 vcc, exec, s[8:9]
	s_cbranch_vccnz .LBB0_941

.LBB0_1653:
	s_ashr_i32 s15, s14, 31
	s_lshl_b64 s[16:17], s[14:15], 19
	s_add_u32 s16, s80, s16
	s_addc_u32 s17, s81, s17
	s_and_b64 s[18:19], s[2:3], exec
	s_cselect_b32 s15, s17, s31
	s_cselect_b32 s47, s16, s30
	s_ashr_i32 s13, s12, 31
	s_lshl_b64 s[18:19], s[12:13], 19
	s_add_u32 s18, s23, s18
	s_addc_u32 s19, s24, s19
	s_and_b64 s[36:37], s[2:3], exec
	s_cselect_b32 s13, s19, s29
	s_cselect_b32 s48, s18, s28
	s_add_u32 s36, s30, 0x40080
	s_addc_u32 s37, s31, 0
	s_add_u32 s49, s28, 0x100
	v_mov_b32_e32 v2, 0
	v_mov_b32_e32 v3, 0
	v_mov_b64_e32 v[4:5], v[2:3]
	v_mov_b64_e32 v[6:7], v[2:3]
	v_mov_b64_e32 v[8:9], v[2:3]
	v_mov_b64_e32 v[10:11], v[2:3]
	v_mov_b64_e32 v[12:13], v[2:3]
	v_mov_b64_e32 v[14:15], v[2:3]
	v_mov_b64_e32 v[16:17], v[2:3]
	v_mov_b64_e32 v[18:19], v[2:3]
	v_mov_b64_e32 v[20:21], v[2:3]
	v_mov_b64_e32 v[22:23], v[2:3]
	v_mov_b64_e32 v[24:25], v[2:3]
	v_mov_b64_e32 v[26:27], v[2:3]
	v_mov_b64_e32 v[28:29], v[2:3]
	v_mov_b64_e32 v[30:31], v[2:3]
	v_mov_b64_e32 v[32:33], v[2:3]
	v_mov_b64_e32 v[34:35], v[2:3]
	v_mov_b64_e32 v[36:37], v[2:3]
	v_mov_b64_e32 v[38:39], v[2:3]
	v_mov_b64_e32 v[40:41], v[2:3]
	v_mov_b64_e32 v[42:43], v[2:3]
	v_mov_b64_e32 v[44:45], v[2:3]
	v_mov_b64_e32 v[46:47], v[2:3]
	v_mov_b64_e32 v[48:49], v[2:3]
	v_mov_b64_e32 v[50:51], v[2:3]
	v_mov_b64_e32 v[52:53], v[2:3]
	v_mov_b64_e32 v[54:55], v[2:3]
	v_mov_b64_e32 v[56:57], v[2:3]
	v_mov_b64_e32 v[58:59], v[2:3]
	v_mov_b64_e32 v[60:61], v[2:3]
	v_mov_b64_e32 v[62:63], v[2:3]
	v_mov_b64_e32 v[64:65], v[2:3]
	v_mov_b64_e32 v[66:67], v[2:3]
	v_mov_b64_e32 v[68:69], v[2:3]
	v_mov_b64_e32 v[70:71], v[2:3]
	v_mov_b64_e32 v[72:73], v[2:3]
	v_mov_b64_e32 v[74:75], v[2:3]
	v_mov_b64_e32 v[76:77], v[2:3]
	v_mov_b64_e32 v[78:79], v[2:3]
	v_mov_b64_e32 v[80:81], v[2:3]
	v_mov_b64_e32 v[82:83], v[2:3]
	v_mov_b64_e32 v[84:85], v[2:3]
	v_mov_b64_e32 v[86:87], v[2:3]
	v_mov_b64_e32 v[88:89], v[2:3]
	v_mov_b64_e32 v[90:91], v[2:3]
	v_mov_b64_e32 v[92:93], v[2:3]
	v_mov_b64_e32 v[94:95], v[2:3]
	v_mov_b64_e32 v[96:97], v[2:3]
	v_mov_b64_e32 v[98:99], v[2:3]
	v_mov_b64_e32 v[100:101], v[2:3]
	v_mov_b64_e32 v[102:103], v[2:3]
	v_mov_b64_e32 v[104:105], v[2:3]
	v_mov_b64_e32 v[106:107], v[2:3]
	v_mov_b64_e32 v[108:109], v[2:3]
	v_mov_b64_e32 v[110:111], v[2:3]
	v_mov_b64_e32 v[112:113], v[2:3]
	v_mov_b64_e32 v[114:115], v[2:3]
	v_mov_b64_e32 v[116:117], v[2:3]
	v_mov_b64_e32 v[118:119], v[2:3]
	v_mov_b64_e32 v[120:121], v[2:3]
	v_mov_b64_e32 v[122:123], v[2:3]
	v_mov_b64_e32 v[124:125], v[2:3]
	v_mov_b64_e32 v[126:127], v[2:3]
	v_mov_b64_e32 v[128:129], v[2:3]
	s_addc_u32 s50, s29, 0
	s_mov_b32 s51, -2
.LBB0_1654:
	ds_read_b128 v[152:155], v131
	ds_read_b128 v[156:159], v131 offset:1024
	ds_read_b128 v[160:163], v131 offset:2048
	ds_read_b128 v[180:183], v131 offset:3072
	ds_read_b128 v[184:187], v176
	ds_read_b128 v[188:191], v176 offset:1024
	ds_read_b128 v[192:195], v176 offset:2048
	ds_read_b128 v[196:199], v176 offset:3072
	s_add_u32 s28, s36, 0xfffc0080
	s_addc_u32 s29, s37, -1
	s_cmp_eq_u32 s51, 12
	s_cselect_b32 s31, s15, s29
	s_cselect_b32 s30, s47, s28
	s_cselect_b32 s29, s13, s50
	s_cselect_b32 s28, s48, s49
	s_add_i32 m0, s33, 0xc000
	ds_read_b128 v[200:203], v177
	ds_read_b128 v[204:207], v177 offset:1024
	ds_read_b128 v[208:211], v177 offset:2048
	ds_read_b128 v[212:215], v177 offset:3072
	ds_read_b128 v[216:219], v177 offset:4096
	ds_read_b128 v[220:223], v177 offset:5120
	ds_read_b128 v[224:227], v177 offset:6144
	ds_read_b128 v[228:231], v177 offset:7168
	global_load_lds_dwordx4 v144, s[36:37]
	s_add_i32 m0, s33, 0xe000
	s_nop 0
	global_load_lds_dwordx4 v146, s[36:37]
	s_waitcnt vmcnt(8)
	s_waitcnt lgkmcnt(0)
	s_barrier
	v_mfma_f32_16x16x32_bf16 v[126:129], v[152:155], v[200:203], v[126:129]
	v_mfma_f32_16x16x32_bf16 v[122:125], v[160:163], v[200:203], v[122:125]
	v_mfma_f32_16x16x32_bf16 v[110:113], v[152:155], v[208:211], v[110:113]
	v_mfma_f32_16x16x32_bf16 v[106:109], v[160:163], v[208:211], v[106:109]
	v_mfma_f32_16x16x32_bf16 v[94:97], v[152:155], v[216:219], v[94:97]
	v_mfma_f32_16x16x32_bf16 v[90:93], v[160:163], v[216:219], v[90:93]
	v_mfma_f32_16x16x32_bf16 v[78:81], v[152:155], v[224:227], v[78:81]
	v_mfma_f32_16x16x32_bf16 v[74:77], v[160:163], v[224:227], v[74:77]
	v_mfma_f32_16x16x32_bf16 v[126:129], v[156:159], v[204:207], v[126:129]
	v_mfma_f32_16x16x32_bf16 v[122:125], v[180:183], v[204:207], v[122:125]
	v_mfma_f32_16x16x32_bf16 v[110:113], v[156:159], v[212:215], v[110:113]
	v_mfma_f32_16x16x32_bf16 v[106:109], v[180:183], v[212:215], v[106:109]
	v_mfma_f32_16x16x32_bf16 v[94:97], v[156:159], v[220:223], v[94:97]
	v_mfma_f32_16x16x32_bf16 v[90:93], v[180:183], v[220:223], v[90:93]
	v_mfma_f32_16x16x32_bf16 v[78:81], v[156:159], v[228:231], v[78:81]
	v_mfma_f32_16x16x32_bf16 v[74:77], v[180:183], v[228:231], v[74:77]
	v_mfma_f32_16x16x32_bf16 v[118:121], v[184:187], v[200:203], v[118:121]
	v_mfma_f32_16x16x32_bf16 v[114:117], v[192:195], v[200:203], v[114:117]
	v_mfma_f32_16x16x32_bf16 v[102:105], v[184:187], v[208:211], v[102:105]
	v_mfma_f32_16x16x32_bf16 v[98:101], v[192:195], v[208:211], v[98:101]
	v_mfma_f32_16x16x32_bf16 v[86:89], v[184:187], v[216:219], v[86:89]
	v_mfma_f32_16x16x32_bf16 v[82:85], v[192:195], v[216:219], v[82:85]
	v_mfma_f32_16x16x32_bf16 v[70:73], v[184:187], v[224:227], v[70:73]
	v_mfma_f32_16x16x32_bf16 v[66:69], v[192:195], v[224:227], v[66:69]
	v_mfma_f32_16x16x32_bf16 v[118:121], v[188:191], v[204:207], v[118:121]
	v_mfma_f32_16x16x32_bf16 v[114:117], v[196:199], v[204:207], v[114:117]
	v_mfma_f32_16x16x32_bf16 v[102:105], v[188:191], v[212:215], v[102:105]
	v_mfma_f32_16x16x32_bf16 v[98:101], v[196:199], v[212:215], v[98:101]
	v_mfma_f32_16x16x32_bf16 v[86:89], v[188:191], v[220:223], v[86:89]
	v_mfma_f32_16x16x32_bf16 v[82:85], v[196:199], v[220:223], v[82:85]
	v_mfma_f32_16x16x32_bf16 v[70:73], v[188:191], v[228:231], v[70:73]
	v_mfma_f32_16x16x32_bf16 v[66:69], v[196:199], v[228:231], v[66:69]
	s_barrier
	s_add_i32 s52, s45, s25
	s_mov_b32 m0, s52
	ds_read_b128 v[200:203], v177 offset:16384
	ds_read_b128 v[204:207], v177 offset:17408
	ds_read_b128 v[208:211], v177 offset:18432
	ds_read_b128 v[212:215], v177 offset:19456
	ds_read_b128 v[216:219], v177 offset:20480
	ds_read_b128 v[220:223], v177 offset:21504
	ds_read_b128 v[224:227], v177 offset:22528
	ds_read_b128 v[228:231], v177 offset:23552
	global_load_lds_dwordx4 v134, s[28:29]
	s_add_i32 m0, s52, 0x2000
	s_add_u32 s52, s28, 0x40000
	s_addc_u32 s53, s29, 0
	s_add_i32 s54, s46, s25
	global_load_lds_dwordx4 v140, s[28:29]
	s_mov_b32 m0, s54
	s_nop 0
	global_load_lds_dwordx4 v134, s[52:53]
	s_add_i32 m0, s54, 0x2000
	s_nop 0
	global_load_lds_dwordx4 v140, s[52:53]
	s_mov_b32 m0, s33
	s_nop 0
	global_load_lds_dwordx4 v132, s[30:31]
	s_mov_b32 m0, s34
	s_nop 0
	global_load_lds_dwordx4 v136, s[30:31]
	s_waitcnt vmcnt(8)
	s_waitcnt lgkmcnt(0)
	s_barrier
	v_mfma_f32_16x16x32_bf16 v[62:65], v[152:155], v[200:203], v[62:65]
	v_mfma_f32_16x16x32_bf16 v[58:61], v[160:163], v[200:203], v[58:61]
	v_mfma_f32_16x16x32_bf16 v[46:49], v[152:155], v[208:211], v[46:49]
	v_mfma_f32_16x16x32_bf16 v[42:45], v[160:163], v[208:211], v[42:45]
	v_mfma_f32_16x16x32_bf16 v[30:33], v[152:155], v[216:219], v[30:33]
	v_mfma_f32_16x16x32_bf16 v[26:29], v[160:163], v[216:219], v[26:29]
	v_mfma_f32_16x16x32_bf16 v[14:17], v[152:155], v[224:227], v[14:17]
	v_mfma_f32_16x16x32_bf16 v[10:13], v[160:163], v[224:227], v[10:13]
	v_mfma_f32_16x16x32_bf16 v[62:65], v[156:159], v[204:207], v[62:65]
	v_mfma_f32_16x16x32_bf16 v[58:61], v[180:183], v[204:207], v[58:61]
	v_mfma_f32_16x16x32_bf16 v[46:49], v[156:159], v[212:215], v[46:49]
	v_mfma_f32_16x16x32_bf16 v[42:45], v[180:183], v[212:215], v[42:45]
	v_mfma_f32_16x16x32_bf16 v[30:33], v[156:159], v[220:223], v[30:33]
	v_mfma_f32_16x16x32_bf16 v[26:29], v[180:183], v[220:223], v[26:29]
	v_mfma_f32_16x16x32_bf16 v[14:17], v[156:159], v[228:231], v[14:17]
	v_mfma_f32_16x16x32_bf16 v[10:13], v[180:183], v[228:231], v[10:13]
	v_mfma_f32_16x16x32_bf16 v[54:57], v[184:187], v[200:203], v[54:57]
	v_mfma_f32_16x16x32_bf16 v[50:53], v[192:195], v[200:203], v[50:53]
	v_mfma_f32_16x16x32_bf16 v[38:41], v[184:187], v[208:211], v[38:41]
	v_mfma_f32_16x16x32_bf16 v[34:37], v[192:195], v[208:211], v[34:37]
	v_mfma_f32_16x16x32_bf16 v[22:25], v[184:187], v[216:219], v[22:25]
	v_mfma_f32_16x16x32_bf16 v[18:21], v[192:195], v[216:219], v[18:21]
	v_mfma_f32_16x16x32_bf16 v[6:9], v[184:187], v[224:227], v[6:9]
	v_mfma_f32_16x16x32_bf16 v[2:5], v[192:195], v[224:227], v[2:5]
	v_mfma_f32_16x16x32_bf16 v[54:57], v[188:191], v[204:207], v[54:57]
	v_mfma_f32_16x16x32_bf16 v[50:53], v[196:199], v[204:207], v[50:53]
	v_mfma_f32_16x16x32_bf16 v[38:41], v[188:191], v[212:215], v[38:41]
	v_mfma_f32_16x16x32_bf16 v[34:37], v[196:199], v[212:215], v[34:37]
	v_mfma_f32_16x16x32_bf16 v[22:25], v[188:191], v[220:223], v[22:25]
	v_mfma_f32_16x16x32_bf16 v[18:21], v[196:199], v[220:223], v[18:21]
	v_mfma_f32_16x16x32_bf16 v[6:9], v[188:191], v[228:231], v[6:9]
	v_mfma_f32_16x16x32_bf16 v[2:5], v[196:199], v[228:231], v[2:5]
	s_barrier
	s_add_i32 s52, 0, 0x18000
	v_add_u32_e32 v179, s52, v175
	s_add_i32 s53, 0, 0x1c000
	ds_read_b128 v[152:155], v179
	ds_read_b128 v[156:159], v179 offset:1024
	ds_read_b128 v[160:163], v179 offset:2048
	ds_read_b128 v[180:183], v179 offset:3072
	v_add_u32_e32 v179, s53, v175
	ds_read_b128 v[184:187], v179
	ds_read_b128 v[188:191], v179 offset:1024
	ds_read_b128 v[192:195], v179 offset:2048
	ds_read_b128 v[196:199], v179 offset:3072
	s_add_u32 s98, s30, 0x40000
	s_addc_u32 s99, s31, 0
	s_mov_b32 m0, s35
	ds_read_b128 v[200:203], v177 offset:32768
	ds_read_b128 v[204:207], v177 offset:33792
	ds_read_b128 v[208:211], v177 offset:34816
	ds_read_b128 v[212:215], v177 offset:35840
	ds_read_b128 v[216:219], v177 offset:36864
	ds_read_b128 v[220:223], v177 offset:37888
	ds_read_b128 v[224:227], v177 offset:38912
	ds_read_b128 v[228:231], v177 offset:39936
	global_load_lds_dwordx4 v132, s[98:99]
	s_mov_b32 m0, s38
	s_nop 0
	global_load_lds_dwordx4 v136, s[98:99]
	s_waitcnt vmcnt(8)
	s_waitcnt lgkmcnt(0)
	s_barrier
	v_mfma_f32_16x16x32_bf16 v[126:129], v[152:155], v[200:203], v[126:129]
	v_mfma_f32_16x16x32_bf16 v[122:125], v[160:163], v[200:203], v[122:125]
	v_mfma_f32_16x16x32_bf16 v[110:113], v[152:155], v[208:211], v[110:113]
	v_mfma_f32_16x16x32_bf16 v[106:109], v[160:163], v[208:211], v[106:109]
	v_mfma_f32_16x16x32_bf16 v[94:97], v[152:155], v[216:219], v[94:97]
	v_mfma_f32_16x16x32_bf16 v[90:93], v[160:163], v[216:219], v[90:93]
	v_mfma_f32_16x16x32_bf16 v[78:81], v[152:155], v[224:227], v[78:81]
	v_mfma_f32_16x16x32_bf16 v[74:77], v[160:163], v[224:227], v[74:77]
	v_mfma_f32_16x16x32_bf16 v[126:129], v[156:159], v[204:207], v[126:129]
	v_mfma_f32_16x16x32_bf16 v[122:125], v[180:183], v[204:207], v[122:125]
	v_mfma_f32_16x16x32_bf16 v[110:113], v[156:159], v[212:215], v[110:113]
	v_mfma_f32_16x16x32_bf16 v[106:109], v[180:183], v[212:215], v[106:109]
	v_mfma_f32_16x16x32_bf16 v[94:97], v[156:159], v[220:223], v[94:97]
	v_mfma_f32_16x16x32_bf16 v[90:93], v[180:183], v[220:223], v[90:93]
	v_mfma_f32_16x16x32_bf16 v[78:81], v[156:159], v[228:231], v[78:81]
	v_mfma_f32_16x16x32_bf16 v[74:77], v[180:183], v[228:231], v[74:77]
	v_mfma_f32_16x16x32_bf16 v[118:121], v[184:187], v[200:203], v[118:121]
	v_mfma_f32_16x16x32_bf16 v[114:117], v[192:195], v[200:203], v[114:117]
	v_mfma_f32_16x16x32_bf16 v[102:105], v[184:187], v[208:211], v[102:105]
	v_mfma_f32_16x16x32_bf16 v[98:101], v[192:195], v[208:211], v[98:101]
	v_mfma_f32_16x16x32_bf16 v[86:89], v[184:187], v[216:219], v[86:89]
	v_mfma_f32_16x16x32_bf16 v[82:85], v[192:195], v[216:219], v[82:85]
	v_mfma_f32_16x16x32_bf16 v[70:73], v[184:187], v[224:227], v[70:73]
	v_mfma_f32_16x16x32_bf16 v[66:69], v[192:195], v[224:227], v[66:69]
	v_mfma_f32_16x16x32_bf16 v[118:121], v[188:191], v[204:207], v[118:121]
	v_mfma_f32_16x16x32_bf16 v[114:117], v[196:199], v[204:207], v[114:117]
	v_mfma_f32_16x16x32_bf16 v[102:105], v[188:191], v[212:215], v[102:105]
	v_mfma_f32_16x16x32_bf16 v[98:101], v[196:199], v[212:215], v[98:101]
	v_mfma_f32_16x16x32_bf16 v[86:89], v[188:191], v[220:223], v[86:89]
	v_mfma_f32_16x16x32_bf16 v[82:85], v[196:199], v[220:223], v[82:85]
	v_mfma_f32_16x16x32_bf16 v[70:73], v[188:191], v[228:231], v[70:73]
	v_mfma_f32_16x16x32_bf16 v[66:69], v[196:199], v[228:231], v[66:69]
	s_barrier
	s_add_i32 s98, s52, s25
	s_add_i32 m0, s98, 0xffffff80
	ds_read_b128 v[200:203], v177 offset:49152
	ds_read_b128 v[204:207], v177 offset:50176
	ds_read_b128 v[208:211], v177 offset:51200
	ds_read_b128 v[212:215], v177 offset:52224
	ds_read_b128 v[216:219], v177 offset:53248
	ds_read_b128 v[220:223], v177 offset:54272
	ds_read_b128 v[224:227], v177 offset:55296
	ds_read_b128 v[228:231], v177 offset:56320
	global_load_lds_dwordx4 v134, s[28:29] offset:128
	s_add_i32 m0, s98, 0x1f80
	s_add_i32 s98, s53, s25
	global_load_lds_dwordx4 v140, s[28:29] offset:128
	s_add_u32 s28, s28, 0x40080
	s_addc_u32 s29, s29, 0
	s_mov_b32 m0, s98
	s_nop 0
	global_load_lds_dwordx4 v134, s[28:29]
	s_add_i32 m0, s98, 0x2000
	s_nop 0
	global_load_lds_dwordx4 v140, s[28:29]
	s_add_i32 m0, s42, 0xffffff80
	s_nop 0
	global_load_lds_dwordx4 v132, s[30:31] offset:128
	s_add_i32 m0, s43, 0xffffff80
	s_nop 0
	global_load_lds_dwordx4 v136, s[30:31] offset:128
	s_waitcnt vmcnt(8)
	s_waitcnt lgkmcnt(0)
	s_barrier
	v_mfma_f32_16x16x32_bf16 v[62:65], v[152:155], v[200:203], v[62:65]
	v_mfma_f32_16x16x32_bf16 v[58:61], v[160:163], v[200:203], v[58:61]
	v_mfma_f32_16x16x32_bf16 v[46:49], v[152:155], v[208:211], v[46:49]
	v_mfma_f32_16x16x32_bf16 v[42:45], v[160:163], v[208:211], v[42:45]
	v_mfma_f32_16x16x32_bf16 v[30:33], v[152:155], v[216:219], v[30:33]
	v_mfma_f32_16x16x32_bf16 v[26:29], v[160:163], v[216:219], v[26:29]
	v_mfma_f32_16x16x32_bf16 v[14:17], v[152:155], v[224:227], v[14:17]
	v_mfma_f32_16x16x32_bf16 v[10:13], v[160:163], v[224:227], v[10:13]
	v_mfma_f32_16x16x32_bf16 v[62:65], v[156:159], v[204:207], v[62:65]
	v_mfma_f32_16x16x32_bf16 v[58:61], v[180:183], v[204:207], v[58:61]
	v_mfma_f32_16x16x32_bf16 v[46:49], v[156:159], v[212:215], v[46:49]
	v_mfma_f32_16x16x32_bf16 v[42:45], v[180:183], v[212:215], v[42:45]
	v_mfma_f32_16x16x32_bf16 v[30:33], v[156:159], v[220:223], v[30:33]
	v_mfma_f32_16x16x32_bf16 v[26:29], v[180:183], v[220:223], v[26:29]
	v_mfma_f32_16x16x32_bf16 v[14:17], v[156:159], v[228:231], v[14:17]
	v_mfma_f32_16x16x32_bf16 v[10:13], v[180:183], v[228:231], v[10:13]
	v_mfma_f32_16x16x32_bf16 v[54:57], v[184:187], v[200:203], v[54:57]
	v_mfma_f32_16x16x32_bf16 v[50:53], v[192:195], v[200:203], v[50:53]
	v_mfma_f32_16x16x32_bf16 v[38:41], v[184:187], v[208:211], v[38:41]
	v_mfma_f32_16x16x32_bf16 v[34:37], v[192:195], v[208:211], v[34:37]
	v_mfma_f32_16x16x32_bf16 v[22:25], v[184:187], v[216:219], v[22:25]
	v_mfma_f32_16x16x32_bf16 v[18:21], v[192:195], v[216:219], v[18:21]
	v_mfma_f32_16x16x32_bf16 v[6:9], v[184:187], v[224:227], v[6:9]
	v_mfma_f32_16x16x32_bf16 v[2:5], v[192:195], v[224:227], v[2:5]
	v_mfma_f32_16x16x32_bf16 v[54:57], v[188:191], v[204:207], v[54:57]
	v_mfma_f32_16x16x32_bf16 v[50:53], v[196:199], v[204:207], v[50:53]
	v_mfma_f32_16x16x32_bf16 v[38:41], v[188:191], v[212:215], v[38:41]
	v_mfma_f32_16x16x32_bf16 v[34:37], v[196:199], v[212:215], v[34:37]
	v_mfma_f32_16x16x32_bf16 v[22:25], v[188:191], v[220:223], v[22:25]
	v_mfma_f32_16x16x32_bf16 v[18:21], v[196:199], v[220:223], v[18:21]
	v_mfma_f32_16x16x32_bf16 v[6:9], v[188:191], v[228:231], v[6:9]
	v_mfma_f32_16x16x32_bf16 v[2:5], v[196:199], v[228:231], v[2:5]
	s_barrier
	s_add_i32 s51, s51, 2
	s_add_u32 s36, s36, 0x100
	s_addc_u32 s37, s37, 0
	s_add_u32 s49, s49, 0x100
	s_addc_u32 s50, s50, 0
	s_cmp_gt_u32 s51, 13
	s_cbranch_scc0 .LBB0_1654
	s_and_b64 vcc, exec, s[10:11]
	s_cbranch_vccz .LBB0_1657
	s_barrier
